# poolprep: hoist the center-row load into the window-load batch (one memory round trip per item instead of two)
# speedup vs baseline: 1.0002x; 1.0002x over previous
; DI unsigned cvtpk(float lo, float hi) { f32x2_t v = {lo, hi}; bf16x2_t b = __builtin_convertvector(v, bf16x2_t); return __builtin_bit_cast(unsigned, b); }
; DI float bflo(unsigned u) { return __uint_as_float(u << 16); }
; DI float bfhi(unsigned u) { return __uint_as_float(u & 0xffff0000u); }
; DI void phase_poolprep(ArgsP a, int tb_, int MR, int vcu, int G) {
;     ...
; #pragma unroll
;         for (int r = 0; r < 16; ++r) { const u32x4 w = wv[r];
;             s[0] += bflo(w.x); s[1] += bfhi(w.x); s[2] += bflo(w.y); s[3] += bfhi(w.y); s[4] += bflo(w.z); s[5] += bfhi(w.z); s[6] += bflo(w.w); s[7] += bfhi(w.w); }
;         const u32x4 w = *(const u32x4*)(zr + (size_t)m * ZR + c8 * 8); const float inv = 1.f / (float)(hi - lo);
;         u32x4 o; o.x = cvtpk(s[0] * inv - bflo(w.x), s[1] * inv - bfhi(w.x)); o.y = cvtpk(s[2] * inv - bflo(w.y), s[3] * inv - bfhi(w.y));
;         o.z = cvtpk(s[4] * inv - bflo(w.z), s[5] * inv - bfhi(w.z)); o.w = cvtpk(s[6] * inv - bflo(w.w), s[7] * inv - bfhi(w.w));
.LBB0_1222:
	s_or_b64 exec, exec, s[12:13]
	s_waitcnt vmcnt(0)
	v_lshlrev_b32_e32 v70, 16, v4
	v_and_b32_e32 v71, 0xffff0000, v4
	v_lshlrev_b32_e32 v4, 16, v5
	v_and_b32_e32 v5, 0xffff0000, v5
	v_lshlrev_b32_e32 v74, 16, v0
	v_and_b32_e32 v75, 0xffff0000, v0
	v_pk_add_f32 v[4:5], v[4:5], 0 op_sel_hi:[1,0]
	v_lshlrev_b32_e32 v0, 16, v1
	v_and_b32_e32 v1, 0xffff0000, v1
	v_pk_add_f32 v[0:1], v[4:5], v[0:1]
	v_lshlrev_b32_e32 v4, 16, v13
	v_and_b32_e32 v5, 0xffff0000, v13
	v_pk_add_f32 v[0:1], v[0:1], v[4:5]
	v_lshlrev_b32_e32 v4, 16, v9
	v_and_b32_e32 v5, 0xffff0000, v9
	v_pk_add_f32 v[0:1], v[0:1], v[4:5]
	v_lshlrev_b32_e32 v4, 16, v21
	v_and_b32_e32 v5, 0xffff0000, v21
	v_pk_add_f32 v[70:71], v[70:71], 0 op_sel_hi:[1,0]
	v_pk_add_f32 v[0:1], v[0:1], v[4:5]
	v_lshlrev_b32_e32 v4, 16, v17
	v_and_b32_e32 v5, 0xffff0000, v17
	v_pk_add_f32 v[70:71], v[70:71], v[74:75]
	v_lshlrev_b32_e32 v74, 16, v12
	v_and_b32_e32 v75, 0xffff0000, v12
	v_pk_add_f32 v[0:1], v[0:1], v[4:5]
	v_lshlrev_b32_e32 v4, 16, v37
	v_and_b32_e32 v5, 0xffff0000, v37
	v_pk_add_f32 v[70:71], v[70:71], v[74:75]
	v_lshlrev_b32_e32 v74, 16, v8
	v_and_b32_e32 v75, 0xffff0000, v8
	v_pk_add_f32 v[8:9], v[0:1], v[4:5]
	v_lshlrev_b32_e32 v0, 16, v6
	v_and_b32_e32 v1, 0xffff0000, v6
	v_pk_add_f32 v[0:1], v[0:1], 0 op_sel_hi:[1,0]
	v_lshlrev_b32_e32 v4, 16, v2
	v_and_b32_e32 v5, 0xffff0000, v2
	v_pk_add_f32 v[0:1], v[0:1], v[4:5]
	v_lshlrev_b32_e32 v4, 16, v14
	v_and_b32_e32 v5, 0xffff0000, v14
	v_pk_add_f32 v[0:1], v[0:1], v[4:5]
	v_lshlrev_b32_e32 v4, 16, v10
	v_and_b32_e32 v5, 0xffff0000, v10
	v_pk_add_f32 v[0:1], v[0:1], v[4:5]
	v_lshlrev_b32_e32 v4, 16, v22
	v_and_b32_e32 v5, 0xffff0000, v22
	v_pk_add_f32 v[0:1], v[0:1], v[4:5]
	v_lshlrev_b32_e32 v4, 16, v18
	v_and_b32_e32 v5, 0xffff0000, v18
	v_pk_add_f32 v[0:1], v[0:1], v[4:5]
	v_lshlrev_b32_e32 v4, 16, v38
	v_and_b32_e32 v5, 0xffff0000, v38
	v_pk_add_f32 v[12:13], v[0:1], v[4:5]
	v_lshlrev_b32_e32 v0, 16, v7
	v_and_b32_e32 v1, 0xffff0000, v7
	v_pk_add_f32 v[0:1], v[0:1], 0 op_sel_hi:[1,0]
	v_lshlrev_b32_e32 v2, 16, v3
	v_and_b32_e32 v3, 0xffff0000, v3
	v_pk_add_f32 v[0:1], v[0:1], v[2:3]
	v_lshlrev_b32_e32 v2, 16, v15
	v_and_b32_e32 v3, 0xffff0000, v15
	v_pk_add_f32 v[0:1], v[0:1], v[2:3]
	v_lshlrev_b32_e32 v2, 16, v11
	v_and_b32_e32 v3, 0xffff0000, v11
	v_pk_add_f32 v[0:1], v[0:1], v[2:3]
	v_lshlrev_b32_e32 v2, 16, v23
	v_and_b32_e32 v3, 0xffff0000, v23
	v_pk_add_f32 v[0:1], v[0:1], v[2:3]
	v_lshlrev_b32_e32 v2, 16, v19
	v_and_b32_e32 v3, 0xffff0000, v19
	v_lshlrev_b32_e32 v18, 16, v52
	v_and_b32_e32 v19, 0xffff0000, v52
	v_cvt_f32_i32_e32 v52, v69
	v_pk_add_f32 v[70:71], v[70:71], v[74:75]
	v_lshlrev_b32_e32 v74, 16, v20
	v_and_b32_e32 v75, 0xffff0000, v20
	v_pk_add_f32 v[0:1], v[0:1], v[2:3]
	v_lshlrev_b32_e32 v2, 16, v39
	v_and_b32_e32 v3, 0xffff0000, v39
	v_lshlrev_b32_e32 v38, 16, v50
	v_and_b32_e32 v39, 0xffff0000, v50
	v_div_scale_f32 v50, s[12:13], v52, v52, 1.0
	v_pk_add_f32 v[70:71], v[70:71], v[74:75]
	v_lshlrev_b32_e32 v74, 16, v16
	v_and_b32_e32 v75, 0xffff0000, v16
	v_lshlrev_b32_e32 v20, 16, v53
	v_and_b32_e32 v21, 0xffff0000, v53
	v_rcp_f32_e32 v53, v50
	v_pk_add_f32 v[70:71], v[70:71], v[74:75]
	v_lshlrev_b32_e32 v74, 16, v36
	v_and_b32_e32 v75, 0xffff0000, v36
	v_pk_add_f32 v[70:71], v[70:71], v[74:75]
	v_pk_add_f32 v[10:11], v[0:1], v[2:3]
	v_lshlrev_b32_e32 v0, 16, v32
	v_and_b32_e32 v1, 0xffff0000, v32
	v_lshlrev_b32_e32 v2, 16, v33
	v_and_b32_e32 v3, 0xffff0000, v33
	v_pk_add_f32 v[0:1], v[70:71], v[0:1]
	v_pk_add_f32 v[2:3], v[8:9], v[2:3]
	v_lshlrev_b32_e32 v14, 16, v34
	v_and_b32_e32 v15, 0xffff0000, v34
	v_lshlrev_b32_e32 v16, 16, v35
	v_and_b32_e32 v17, 0xffff0000, v35
	v_lshlrev_b32_e32 v34, 16, v48
	v_and_b32_e32 v35, 0xffff0000, v48
	v_lshlrev_b32_e32 v36, 16, v49
	v_and_b32_e32 v37, 0xffff0000, v49
	v_lshlrev_b32_e32 v48, 16, v51
	v_and_b32_e32 v49, 0xffff0000, v51
	v_fma_f32 v51, -v50, v53, 1.0
	v_pk_add_f32 v[0:1], v[0:1], v[18:19]
	v_pk_add_f32 v[2:3], v[2:3], v[20:21]
	v_fmac_f32_e32 v53, v51, v53
	v_div_scale_f32 v51, vcc, 1.0, v52, 1.0
	v_pk_add_f32 v[0:1], v[0:1], v[34:35]
	v_lshlrev_b32_e32 v18, 16, v28
	v_and_b32_e32 v19, 0xffff0000, v28
	v_pk_add_f32 v[2:3], v[2:3], v[36:37]
	v_lshlrev_b32_e32 v8, 16, v29
	v_and_b32_e32 v9, 0xffff0000, v29
	v_lshlrev_b32_e32 v22, 16, v54
	v_and_b32_e32 v23, 0xffff0000, v54
	v_mul_f32_e32 v54, v51, v53
	v_pk_add_f32 v[0:1], v[0:1], v[18:19]
	v_lshlrev_b32_e32 v18, 16, v24
	v_and_b32_e32 v19, 0xffff0000, v24
	v_pk_add_f32 v[2:3], v[2:3], v[8:9]
	v_lshlrev_b32_e32 v8, 16, v25
	v_and_b32_e32 v9, 0xffff0000, v25
	v_lshlrev_b32_e32 v32, 16, v55
	v_and_b32_e32 v33, 0xffff0000, v55
	v_fma_f32 v55, -v50, v54, v51
	v_pk_add_f32 v[0:1], v[0:1], v[18:19]
	v_lshlrev_b32_e32 v18, 16, v44
	v_and_b32_e32 v19, 0xffff0000, v44
	v_pk_add_f32 v[2:3], v[2:3], v[8:9]
	v_lshlrev_b32_e32 v8, 16, v45
	v_and_b32_e32 v9, 0xffff0000, v45
	v_fmac_f32_e32 v54, v55, v53
	v_pk_add_f32 v[0:1], v[0:1], v[18:19]
	v_lshlrev_b32_e32 v18, 16, v40
	v_and_b32_e32 v19, 0xffff0000, v40
	v_pk_add_f32 v[2:3], v[2:3], v[8:9]
	v_lshlrev_b32_e32 v8, 16, v41
	v_and_b32_e32 v9, 0xffff0000, v41
	v_fma_f32 v50, -v50, v54, v51
	v_pk_add_f32 v[0:1], v[0:1], v[18:19]
	v_lshlrev_b32_e32 v18, 16, v60
	v_and_b32_e32 v19, 0xffff0000, v60
	v_pk_add_f32 v[2:3], v[2:3], v[8:9]
	v_lshlrev_b32_e32 v8, 16, v61
	v_and_b32_e32 v9, 0xffff0000, v61
	v_div_fmas_f32 v50, v50, v53, v54
	v_pk_add_f32 v[0:1], v[0:1], v[18:19]
	v_lshlrev_b32_e32 v18, 16, v56
	v_and_b32_e32 v19, 0xffff0000, v56
	v_pk_add_f32 v[2:3], v[2:3], v[8:9]
	v_lshlrev_b32_e32 v8, 16, v57
	v_and_b32_e32 v9, 0xffff0000, v57
	v_div_fixup_f32 v50, v50, v52, 1.0
	v_pk_add_f32 v[0:1], v[0:1], v[18:19]
	s_waitcnt vmcnt(0)
; DI unsigned cvtpk(float lo, float hi) { f32x2_t v = {lo, hi}; bf16x2_t b = __builtin_convertvector(v, bf16x2_t); return __builtin_bit_cast(unsigned, b); }
; DI float bflo(unsigned u) { return __uint_as_float(u << 16); }
; DI float bfhi(unsigned u) { return __uint_as_float(u & 0xffff0000u); }
; DI void phase_poolprep(ArgsP a, int tb_, int MR, int vcu, int G) {
;     ...
;     for (int i = gt; i < MR * 64; i += NGT) {
;         const int m = i >> 6, c8 = i & 63, w2 = 1 << (c8 >> 4);
;         const bool lat = m < ML; const int t = lat ? (m & 4095) : ((m - ML) & 255), Ls = lat ? SEQ : LC, mb = m - t;
;         const int lo = max(t - w2, 0), hi = min(t + w2, Ls);
;         float s[8];
; #pragma unroll
;         for (int j = 0; j < 8; ++j) s[j] = 0.f;
;         const int cnt = hi - lo; const bf16_t* zp = zr + (size_t)(mb + lo) * ZR + c8 * 8;
;         u32x4 wv[16];
; #pragma unroll
;         for (int r = 0; r < 16; ++r) { wv[r] = (u32x4){0u, 0u, 0u, 0u}; if (r < cnt) wv[r] = *(const u32x4*)(zp + (size_t)r * ZR); }
; #pragma unroll
;         for (int r = 0; r < 16; ++r) { const u32x4 w = wv[r];
;             s[0] += bflo(w.x); s[1] += bfhi(w.x); s[2] += bflo(w.y); s[3] += bfhi(w.y); s[4] += bflo(w.z); s[5] += bfhi(w.z); s[6] += bflo(w.w); s[7] += bfhi(w.w); }
;         const u32x4 w = *(const u32x4*)(zr + (size_t)m * ZR + c8 * 8); const float inv = 1.f / (float)(hi - lo);
;         u32x4 o; o.x = cvtpk(s[0] * inv - bflo(w.x), s[1] * inv - bfhi(w.x)); o.y = cvtpk(s[2] * inv - bflo(w.y), s[3] * inv - bfhi(w.y));
;         o.z = cvtpk(s[4] * inv - bflo(w.z), s[5] * inv - bfhi(w.z)); o.w = cvtpk(s[6] * inv - bflo(w.w), s[7] * inv - bfhi(w.w));
;         *(u32x4*)(pz + (size_t)m * 512 + c8 * 8) = o;
	v_lshlrev_b32_e32 v18, 16, v76
	v_and_b32_e32 v19, 0xffff0000, v76
	v_pk_add_f32 v[2:3], v[2:3], v[8:9]
	v_lshlrev_b32_e32 v4, 16, v77
	v_and_b32_e32 v5, 0xffff0000, v77
	v_pk_fma_f32 v[0:1], v[50:51], v[0:1], v[18:19] op_sel_hi:[0,1,1] neg_lo:[0,0,1] neg_hi:[0,0,1]
	v_pk_fma_f32 v[2:3], v[50:51], v[2:3], v[4:5] op_sel_hi:[0,1,1] neg_lo:[0,0,1] neg_hi:[0,0,1]
	v_cvt_pk_bf16_f32 v0, v0, v1
	v_cvt_pk_bf16_f32 v1, v2, v3
	v_pk_add_f32 v[2:3], v[12:13], v[14:15]
	v_lshlrev_b32_e32 v4, 16, v30
	v_pk_add_f32 v[2:3], v[2:3], v[22:23]
	v_and_b32_e32 v5, 0xffff0000, v30
	v_pk_add_f32 v[2:3], v[2:3], v[38:39]
	v_lshlrev_b32_e32 v8, 16, v31
	v_pk_add_f32 v[2:3], v[2:3], v[4:5]
	v_lshlrev_b32_e32 v4, 16, v26
	v_and_b32_e32 v5, 0xffff0000, v26
	v_pk_add_f32 v[2:3], v[2:3], v[4:5]
	v_lshlrev_b32_e32 v4, 16, v46
	v_and_b32_e32 v5, 0xffff0000, v46
	v_pk_add_f32 v[2:3], v[2:3], v[4:5]
	v_lshlrev_b32_e32 v4, 16, v42
	v_and_b32_e32 v5, 0xffff0000, v42
	v_pk_add_f32 v[2:3], v[2:3], v[4:5]
	v_lshlrev_b32_e32 v4, 16, v62
	v_and_b32_e32 v5, 0xffff0000, v62
	v_pk_add_f32 v[2:3], v[2:3], v[4:5]
	v_lshlrev_b32_e32 v4, 16, v58
	v_and_b32_e32 v5, 0xffff0000, v58
	v_pk_add_f32 v[2:3], v[2:3], v[4:5]
	v_lshlrev_b32_e32 v4, 16, v78
	v_and_b32_e32 v5, 0xffff0000, v78
	v_pk_fma_f32 v[2:3], v[50:51], v[2:3], v[4:5] op_sel_hi:[0,1,1] neg_lo:[0,0,1] neg_hi:[0,0,1]
	v_pk_add_f32 v[4:5], v[10:11], v[16:17]
	v_and_b32_e32 v9, 0xffff0000, v31
	v_pk_add_f32 v[4:5], v[4:5], v[32:33]
	v_lshlrev_b32_e32 v6, 16, v79
	v_pk_add_f32 v[4:5], v[4:5], v[48:49]
	v_and_b32_e32 v7, 0xffff0000, v79
	v_pk_add_f32 v[4:5], v[4:5], v[8:9]
	v_lshlrev_b32_e32 v8, 16, v27
	v_and_b32_e32 v9, 0xffff0000, v27
	v_pk_add_f32 v[4:5], v[4:5], v[8:9]
	v_lshlrev_b32_e32 v8, 16, v47
	v_and_b32_e32 v9, 0xffff0000, v47
	v_pk_add_f32 v[4:5], v[4:5], v[8:9]
	v_lshlrev_b32_e32 v8, 16, v43
	v_and_b32_e32 v9, 0xffff0000, v43
	v_pk_add_f32 v[4:5], v[4:5], v[8:9]
	v_lshlrev_b32_e32 v8, 16, v63
	v_and_b32_e32 v9, 0xffff0000, v63
	v_pk_add_f32 v[4:5], v[4:5], v[8:9]
	v_lshlrev_b32_e32 v8, 16, v59
	v_and_b32_e32 v9, 0xffff0000, v59
	v_pk_add_f32 v[4:5], v[4:5], v[8:9]
	v_ashrrev_i32_e32 v69, 31, v68
	v_pk_fma_f32 v[4:5], v[50:51], v[4:5], v[6:7] op_sel_hi:[0,1,1] neg_lo:[0,0,1] neg_hi:[0,0,1]
	v_add_u32_e32 v72, s14, v72
	v_cvt_pk_bf16_f32 v2, v2, v3
	v_cvt_pk_bf16_f32 v3, v4, v5
	v_lshlrev_b64 v[4:5], 10, v[68:69]
	v_cmp_le_i32_e32 vcc, s4, v72
	v_lshl_add_u64 v[4:5], v[66:67], 0, v[4:5]
	s_or_b64 s[10:11], vcc, s[10:11]
	global_store_dwordx4 v[4:5], v[0:3], off
	s_andn2_b64 exec, exec, s[10:11]
	s_cbranch_execz .LBB0_1255
.LBB0_1223:
	v_ashrrev_i32_e32 v68, 6, v72
	v_mad_i64_i32 v[76:77], s[12:13], v68, s67, v[64:65]
	global_load_dwordx4 v[76:79], v[76:77], off
	v_cmp_gt_i32_e32 vcc, s74, v68
	v_mov_b32_e32 v3, 0x100
	v_mov_b32_e32 v4, 0x1000
	v_cndmask_b32_e32 v0, v238, v239, vcc
	v_and_b32_e32 v0, v0, v68
	v_sub_u32_e32 v1, v0, v73
	v_add_u32_e32 v2, v0, v73
	v_cndmask_b32_e32 v3, v3, v4, vcc
	v_sub_u32_e32 v4, v68, v0
	v_max_i32_e32 v1, 0, v1
	v_min_u32_e32 v2, v2, v3
	v_sub_u32_e32 v69, v2, v1
	v_add_u32_e32 v1, v4, v1
	v_mov_b32_e32 v0, 0
	v_mad_i64_i32 v[70:71], s[12:13], v1, s67, v[64:65]
	v_cmp_lt_i32_e32 vcc, 0, v69
	v_mov_b32_e32 v4, 0
	v_mov_b32_e32 v5, 0
	v_mov_b32_e32 v6, 0
	v_mov_b32_e32 v7, 0
	s_and_saveexec_b64 s[12:13], vcc
	s_cbranch_execz .LBB0_1225
	global_load_dwordx4 v[4:7], v[70:71], off
